# code warm-up extended: waves 1-7 cover [pc, pc+28K) (+28K more at barriers 1-6), and the kernel entry touches the first 64 KiB of code
# speedup vs baseline: 1.0149x; 1.0025x over previous
; DI unsigned xb_add(unsigned* p, unsigned v) { return __hip_atomic_fetch_add(p, v, __ATOMIC_RELAXED, __HIP_MEMORY_SCOPE_AGENT); }
; DI unsigned xb_xcc_id() { return (unsigned)__builtin_amdgcn_s_getreg((3 << 11) | 20) & 0xFu; }
; __global__ void __launch_bounds__(512, 2) fwd_megakernel(Params p) {
;     extern __shared__ __attribute__((aligned(16))) unsigned char lds[];
;     cg::grid_group grid = cg::this_grid();
;     unsigned* bar = (unsigned*)(p.ws + OFF_BAR);
;     __shared__ __attribute__((aligned(16))) unsigned xb_st[4];
;     volatile __attribute__((address_space(3))) unsigned* st = (volatile __attribute__((address_space(3))) unsigned*)xb_st;
;     if (threadIdx.x < 4) xb_st[threadIdx.x] = 0u;
;     __syncthreads();
;     if (threadIdx.x == 0) (void)xb_add(&bar[XB_XCNT(xb_xcc_id())], 1u);
_Z14fwd_megakernel6Params:
	s_load_dwordx16 s[56:71], s[0:1], 0xc0
	s_add_u32 s4, s0, 0x100
	s_addc_u32 s5, s1, 0
	v_and_b32_e32 v250, 0x3ff, v0
	s_getpc_b64 vcc
	v_lshlrev_b32_e32 v253, 6, v250
	v_mov_b32_e32 v248, vcc_lo
	v_mov_b32_e32 v249, vcc_hi
	v_add_co_u32_e32 v248, vcc, v248, v253
	s_nop 1
	v_addc_co_u32_e32 v249, vcc, 0, v249, vcc
	global_load_dword v251, v[248:249], off
	v_add_co_u32_e32 v248, vcc, 0x8000, v248
	s_nop 1
	v_addc_co_u32_e32 v249, vcc, 0, v249, vcc
	global_load_dword v252, v[248:249], off
	v_writelane_b32 v254, s4, 0
	v_cmp_gt_u32_e32 vcc, 4, v250
	s_nop 0
	v_writelane_b32 v254, s5, 1
	s_and_saveexec_b64 s[4:5], vcc
	v_lshlrev_b32_e32 v1, 2, v250
	v_mov_b32_e32 v2, 0
	ds_write_b32 v1, v2
	s_or_b64 exec, exec, s[4:5]
	s_load_dword s33, s[0:1], 0x100
	s_waitcnt lgkmcnt(0)
	s_add_u32 s4, s70, 0x34e2100
	s_addc_u32 s5, s71, 0
	v_writelane_b32 v254, s4, 2
	v_cmp_eq_u32_e32 vcc, 0, v250
	s_nop 0
	v_writelane_b32 v254, s5, 3
	s_barrier
	s_and_saveexec_b64 s[4:5], vcc
	s_cbranch_execz .LBB0_5
	s_mov_b64 s[6:7], exec
	v_mbcnt_lo_u32_b32 v1, s6, 0
	v_mbcnt_hi_u32_b32 v1, s7, v1
	v_cmp_eq_u32_e32 vcc, 0, v1
	s_getreg_b32 s3, hwreg(HW_REG_XCC_ID, 0, 4)
	s_and_b64 s[8:9], exec, vcc
	s_mov_b64 exec, s[8:9]
	s_cbranch_execz .LBB0_5
	s_lshl_b32 s3, s3, 8
	s_bcnt1_i32_b64 s6, s[6:7]
	s_and_b32 s3, s3, 0xf00
	v_mov_b32_e32 v2, s6
	v_readlane_b32 s6, v254, 2
	v_mov_b32_e32 v1, s3
	v_readlane_b32 s7, v254, 3
	s_nop 4
	global_atomic_add v1, v2, s[6:7] offset:1024

; DI int fresh_tid() { int t = threadIdx.x; asm volatile("" : "+v"(t)); return t; }
; DI void xcd_barrier(unsigned* bar, volatile __attribute__((address_space(3))) unsigned* st) {
;     asm volatile("s_waitcnt vmcnt(0)" ::: "memory");
;     __syncthreads();
;     if (fresh_tid() == 0) {
.LBB0_132:
	s_or_b64 exec, exec, s[6:7]
	s_waitcnt vmcnt(0)
	v_mov_b32_e32 v0, v250
	s_barrier
	s_getpc_b64 vcc
	v_mov_b32_e32 v2, vcc_lo
	v_mov_b32_e32 v3, vcc_hi
	v_cmp_lt_u32_e32 vcc, 63, v0
	s_and_saveexec_b64 s[0:1], vcc
	s_cbranch_execz .Lcpf_s1
	v_lshlrev_b32_e32 v1, 6, v0
	v_subrev_u32_e32 v1, 0x1000, v1
	v_add_co_u32_e32 v2, vcc, v2, v1
	s_nop 1
	v_addc_co_u32_e32 v3, vcc, 0, v3, vcc
	global_load_dword v4, v[2:3], off
	v_add_co_u32_e32 v2, vcc, 0x7000, v2
	s_nop 1
	v_addc_co_u32_e32 v3, vcc, 0, v3, vcc
	global_load_dword v5, v[2:3], off

; DI int fresh_tid() { int t = threadIdx.x; asm volatile("" : "+v"(t)); return t; }
; DI void xcd_barrier(unsigned* bar, volatile __attribute__((address_space(3))) unsigned* st) {
;     asm volatile("s_waitcnt vmcnt(0)" ::: "memory");
;     __syncthreads();
;     if (fresh_tid() == 0) {
.LBB0_222:
	s_or_b64 exec, exec, s[0:1]
	s_waitcnt vmcnt(0)
	v_mov_b32_e32 v0, v250
	s_barrier
	s_getpc_b64 vcc
	v_mov_b32_e32 v2, vcc_lo
	v_mov_b32_e32 v3, vcc_hi
	v_cmp_lt_u32_e32 vcc, 63, v0
	s_and_saveexec_b64 s[0:1], vcc
	s_cbranch_execz .Lcpf_s2
	v_lshlrev_b32_e32 v1, 6, v0
	v_subrev_u32_e32 v1, 0x1000, v1
	v_add_co_u32_e32 v2, vcc, v2, v1
	s_nop 1
	v_addc_co_u32_e32 v3, vcc, 0, v3, vcc
	global_load_dword v4, v[2:3], off
	v_add_co_u32_e32 v2, vcc, 0x7000, v2
	s_nop 1
	v_addc_co_u32_e32 v3, vcc, 0, v3, vcc
	global_load_dword v5, v[2:3], off

; DI int fresh_tid() { int t = threadIdx.x; asm volatile("" : "+v"(t)); return t; }
; DI void xcd_barrier(unsigned* bar, volatile __attribute__((address_space(3))) unsigned* st) {
;     asm volatile("s_waitcnt vmcnt(0)" ::: "memory");
;     __syncthreads();
;     if (fresh_tid() == 0) {
.LBB0_305:
	s_waitcnt vmcnt(0)
	v_mov_b32_e32 v0, v250
	s_waitcnt lgkmcnt(0)
	s_barrier
	s_getpc_b64 vcc
	v_mov_b32_e32 v2, vcc_lo
	v_mov_b32_e32 v3, vcc_hi
	v_cmp_lt_u32_e32 vcc, 63, v0
	s_and_saveexec_b64 s[0:1], vcc
	s_cbranch_execz .Lcpf_s3
	v_lshlrev_b32_e32 v1, 6, v0
	v_subrev_u32_e32 v1, 0x1000, v1
	v_add_co_u32_e32 v2, vcc, v2, v1
	s_nop 1
	v_addc_co_u32_e32 v3, vcc, 0, v3, vcc
	global_load_dword v4, v[2:3], off
	v_add_co_u32_e32 v2, vcc, 0x7000, v2
	s_nop 1
	v_addc_co_u32_e32 v3, vcc, 0, v3, vcc
	global_load_dword v5, v[2:3], off

; DI int fresh_tid() { int t = threadIdx.x; asm volatile("" : "+v"(t)); return t; }
; DI void xcd_barrier(unsigned* bar, volatile __attribute__((address_space(3))) unsigned* st) {
;     asm volatile("s_waitcnt vmcnt(0)" ::: "memory");
;     __syncthreads();
;     if (fresh_tid() == 0) {
.LBB0_382:
	s_or_b64 exec, exec, s[16:17]
	s_waitcnt vmcnt(0)
	v_mov_b32_e32 v0, v250
	s_waitcnt lgkmcnt(0)
	s_barrier
	s_getpc_b64 vcc
	v_mov_b32_e32 v2, vcc_lo
	v_mov_b32_e32 v3, vcc_hi
	v_cmp_lt_u32_e32 vcc, 63, v0
	s_and_saveexec_b64 s[0:1], vcc
	s_cbranch_execz .Lcpf_s4
	v_lshlrev_b32_e32 v1, 6, v0
	v_subrev_u32_e32 v1, 0x1000, v1
	v_add_co_u32_e32 v2, vcc, v2, v1
	s_nop 1
	v_addc_co_u32_e32 v3, vcc, 0, v3, vcc
	global_load_dword v4, v[2:3], off
	v_add_co_u32_e32 v2, vcc, 0x7000, v2
	s_nop 1
	v_addc_co_u32_e32 v3, vcc, 0, v3, vcc
	global_load_dword v5, v[2:3], off

; DI int fresh_tid() { int t = threadIdx.x; asm volatile("" : "+v"(t)); return t; }
; DI void xcd_barrier(unsigned* bar, volatile __attribute__((address_space(3))) unsigned* st) {
;     asm volatile("s_waitcnt vmcnt(0)" ::: "memory");
;     __syncthreads();
;     if (fresh_tid() == 0) {
.LBB0_472:
	s_waitcnt vmcnt(0)
	v_mov_b32_e32 v0, v250
	s_waitcnt vmcnt(0) lgkmcnt(0)
	s_barrier
	s_getpc_b64 vcc
	v_mov_b32_e32 v2, vcc_lo
	v_mov_b32_e32 v3, vcc_hi
	v_cmp_lt_u32_e32 vcc, 63, v0
	s_and_saveexec_b64 s[0:1], vcc
	s_cbranch_execz .Lcpf_s5
	v_lshlrev_b32_e32 v1, 6, v0
	v_subrev_u32_e32 v1, 0x1000, v1
	v_add_co_u32_e32 v2, vcc, v2, v1
	s_nop 1
	v_addc_co_u32_e32 v3, vcc, 0, v3, vcc
	global_load_dword v4, v[2:3], off
	v_add_co_u32_e32 v2, vcc, 0x7000, v2
	s_nop 1
	v_addc_co_u32_e32 v3, vcc, 0, v3, vcc
	global_load_dword v5, v[2:3], off

; DI int fresh_tid() { int t = threadIdx.x; asm volatile("" : "+v"(t)); return t; }
; DI void xcd_barrier(unsigned* bar, volatile __attribute__((address_space(3))) unsigned* st) {
;     asm volatile("s_waitcnt vmcnt(0)" ::: "memory");
;     __syncthreads();
;     if (fresh_tid() == 0) {
.LBB0_580:
	s_or_b64 exec, exec, s[8:9]
	s_waitcnt vmcnt(0)
	v_mov_b32_e32 v0, v250
	s_barrier
	s_getpc_b64 vcc
	v_mov_b32_e32 v2, vcc_lo
	v_mov_b32_e32 v3, vcc_hi
	v_cmp_lt_u32_e32 vcc, 63, v0
	s_and_saveexec_b64 s[0:1], vcc
	s_cbranch_execz .Lcpf_s6
	v_lshlrev_b32_e32 v1, 6, v0
	v_subrev_u32_e32 v1, 0x1000, v1
	v_add_co_u32_e32 v2, vcc, v2, v1
	s_nop 1
	v_addc_co_u32_e32 v3, vcc, 0, v3, vcc
	global_load_dword v4, v[2:3], off
	v_add_co_u32_e32 v2, vcc, 0x7000, v2
	s_nop 1
	v_addc_co_u32_e32 v3, vcc, 0, v3, vcc
	global_load_dword v5, v[2:3], off

; DI int fresh_tid() { int t = threadIdx.x; asm volatile("" : "+v"(t)); return t; }
; DI void xcd_barrier(unsigned* bar, volatile __attribute__((address_space(3))) unsigned* st) {
;     asm volatile("s_waitcnt vmcnt(0)" ::: "memory");
;     __syncthreads();
;     if (fresh_tid() == 0) {
.LBB0_662:
	s_waitcnt vmcnt(0)
	v_mov_b32_e32 v0, v250
	s_waitcnt vmcnt(0)
	s_barrier
	s_getpc_b64 vcc
	v_mov_b32_e32 v2, vcc_lo
	v_mov_b32_e32 v3, vcc_hi
	v_cmp_lt_u32_e32 vcc, 63, v0
	s_and_saveexec_b64 s[0:1], vcc
	s_cbranch_execz .Lcpf_s7
	v_lshlrev_b32_e32 v1, 6, v0
	v_subrev_u32_e32 v1, 0x1000, v1
	v_add_co_u32_e32 v2, vcc, v2, v1
	s_nop 1
	v_addc_co_u32_e32 v3, vcc, 0, v3, vcc
	global_load_dword v4, v[2:3], off

; DI int fresh_tid() { int t = threadIdx.x; asm volatile("" : "+v"(t)); return t; }
; DI void xcd_barrier(unsigned* bar, volatile __attribute__((address_space(3))) unsigned* st) {
;     asm volatile("s_waitcnt vmcnt(0)" ::: "memory");
;     __syncthreads();
;     if (fresh_tid() == 0) {
.LBB0_783:
	v_readlane_b32 s0, v255, 2
	v_readlane_b32 s1, v255, 3
	s_or_b64 exec, exec, s[0:1]
	s_waitcnt vmcnt(0)
	v_mov_b32_e32 v0, v250
	s_barrier
	s_getpc_b64 vcc
	v_mov_b32_e32 v2, vcc_lo
	v_mov_b32_e32 v3, vcc_hi
	v_cmp_lt_u32_e32 vcc, 63, v0
	s_and_saveexec_b64 s[0:1], vcc
	s_cbranch_execz .Lcpf_s8
	v_lshlrev_b32_e32 v1, 6, v0
	v_subrev_u32_e32 v1, 0x1000, v1
	v_add_co_u32_e32 v2, vcc, v2, v1
	s_nop 1
	v_addc_co_u32_e32 v3, vcc, 0, v3, vcc
	global_load_dword v4, v[2:3], off

; DI int fresh_tid() { int t = threadIdx.x; asm volatile("" : "+v"(t)); return t; }
; DI void xcd_barrier(unsigned* bar, volatile __attribute__((address_space(3))) unsigned* st) {
;     asm volatile("s_waitcnt vmcnt(0)" ::: "memory");
;     __syncthreads();
;     if (fresh_tid() == 0) {
.LBB0_859:
	s_waitcnt vmcnt(0)
	v_mov_b32_e32 v0, v250
	s_barrier
	s_getpc_b64 vcc
	v_mov_b32_e32 v2, vcc_lo
	v_mov_b32_e32 v3, vcc_hi
	v_cmp_lt_u32_e32 vcc, 63, v0
	s_and_saveexec_b64 s[4:5], vcc
	s_cbranch_execz .Lcpf_s9
	v_lshlrev_b32_e32 v1, 6, v0
	v_subrev_u32_e32 v1, 0x1000, v1
	v_add_co_u32_e32 v2, vcc, v2, v1
	s_nop 1
	v_addc_co_u32_e32 v3, vcc, 0, v3, vcc
	global_load_dword v4, v[2:3], off

; DI int fresh_tid() { int t = threadIdx.x; asm volatile("" : "+v"(t)); return t; }
; DI void xcd_barrier(unsigned* bar, volatile __attribute__((address_space(3))) unsigned* st) {
;     asm volatile("s_waitcnt vmcnt(0)" ::: "memory");
;     __syncthreads();
;     if (fresh_tid() == 0) {
.LBB0_935:
	s_waitcnt vmcnt(0)
	v_mov_b32_e32 v0, v250
	s_barrier
	s_getpc_b64 vcc
	v_mov_b32_e32 v2, vcc_lo
	v_mov_b32_e32 v3, vcc_hi
	v_cmp_lt_u32_e32 vcc, 63, v0
	s_and_saveexec_b64 s[4:5], vcc
	s_cbranch_execz .Lcpf_s10
	v_lshlrev_b32_e32 v1, 6, v0
	v_subrev_u32_e32 v1, 0x1000, v1
	v_min_u32_e32 v1, 0x6d80, v1
	v_add_co_u32_e32 v2, vcc, v2, v1
	s_nop 1
	v_addc_co_u32_e32 v3, vcc, 0, v3, vcc
	global_load_dword v4, v[2:3], off

; DI int fresh_tid() { int t = threadIdx.x; asm volatile("" : "+v"(t)); return t; }
; DI void xcd_barrier(unsigned* bar, volatile __attribute__((address_space(3))) unsigned* st) {
;     asm volatile("s_waitcnt vmcnt(0)" ::: "memory");
;     __syncthreads();
;     if (fresh_tid() == 0) {
.LBB0_998:
	s_or_b64 exec, exec, s[6:7]
	s_waitcnt vmcnt(0)
	v_mov_b32_e32 v0, v250
	s_barrier
	s_getpc_b64 vcc
	v_mov_b32_e32 v2, vcc_lo
	v_mov_b32_e32 v3, vcc_hi
	v_cmp_lt_u32_e32 vcc, 63, v0
	s_and_saveexec_b64 s[4:5], vcc
	s_cbranch_execz .Lcpf_s11
	v_lshlrev_b32_e32 v1, 6, v0
	v_subrev_u32_e32 v1, 0x1000, v1
	v_min_u32_e32 v1, 0x5480, v1
	v_add_co_u32_e32 v2, vcc, v2, v1
	s_nop 1
	v_addc_co_u32_e32 v3, vcc, 0, v3, vcc
	global_load_dword v4, v[2:3], off

; DI int fresh_tid() { int t = threadIdx.x; asm volatile("" : "+v"(t)); return t; }
; DI void xcd_barrier(unsigned* bar, volatile __attribute__((address_space(3))) unsigned* st) {
;     asm volatile("s_waitcnt vmcnt(0)" ::: "memory");
;     __syncthreads();
;     if (fresh_tid() == 0) {
.LBB0_1092:
	s_waitcnt vmcnt(0)
	v_mov_b32_e32 v0, v250
	s_barrier
	s_getpc_b64 vcc
	v_mov_b32_e32 v2, vcc_lo
	v_mov_b32_e32 v3, vcc_hi
	v_cmp_lt_u32_e32 vcc, 63, v0
	s_and_saveexec_b64 s[4:5], vcc
	s_cbranch_execz .Lcpf_s12
	v_lshlrev_b32_e32 v1, 6, v0
	v_subrev_u32_e32 v1, 0x1000, v1
	v_min_u32_e32 v1, 0x3180, v1
	v_add_co_u32_e32 v2, vcc, v2, v1
	s_nop 1
	v_addc_co_u32_e32 v3, vcc, 0, v3, vcc
	global_load_dword v4, v[2:3], off

; DI int fresh_tid() { int t = threadIdx.x; asm volatile("" : "+v"(t)); return t; }
; DI void xcd_barrier(unsigned* bar, volatile __attribute__((address_space(3))) unsigned* st) {
;     asm volatile("s_waitcnt vmcnt(0)" ::: "memory");
;     __syncthreads();
;     if (fresh_tid() == 0) {
.LBB0_1151:
	s_or_b64 exec, exec, s[6:7]
	s_waitcnt vmcnt(0)
	v_mov_b32_e32 v0, v250
	s_barrier
	s_getpc_b64 vcc
	v_mov_b32_e32 v2, vcc_lo
	v_mov_b32_e32 v3, vcc_hi
	v_cmp_lt_u32_e32 vcc, 63, v0
	s_and_saveexec_b64 s[4:5], vcc
	s_cbranch_execz .Lcpf_s13
	v_lshlrev_b32_e32 v1, 6, v0
	v_subrev_u32_e32 v1, 0x1000, v1
	v_min_u32_e32 v1, 0x29c0, v1
	v_add_co_u32_e32 v2, vcc, v2, v1
	s_nop 1
	v_addc_co_u32_e32 v3, vcc, 0, v3, vcc
	global_load_dword v4, v[2:3], off

; DI int fresh_tid() { int t = threadIdx.x; asm volatile("" : "+v"(t)); return t; }
; DI void xcd_barrier(unsigned* bar, volatile __attribute__((address_space(3))) unsigned* st) {
;     asm volatile("s_waitcnt vmcnt(0)" ::: "memory");
;     __syncthreads();
;     if (fresh_tid() == 0) {
.LBB0_1231:
	s_waitcnt vmcnt(0)
	v_mov_b32_e32 v0, v250
	s_barrier
	s_getpc_b64 vcc
	v_mov_b32_e32 v2, vcc_lo
	v_mov_b32_e32 v3, vcc_hi
	v_cmp_lt_u32_e32 vcc, 63, v0
	s_and_saveexec_b64 s[0:1], vcc
	s_cbranch_execz .Lcpf_s14
	v_lshlrev_b32_e32 v1, 6, v0
	v_subrev_u32_e32 v1, 0x1000, v1
	v_min_u32_e32 v1, 0xe40, v1
	v_add_co_u32_e32 v2, vcc, v2, v1
	s_nop 1
	v_addc_co_u32_e32 v3, vcc, 0, v3, vcc
	global_load_dword v4, v[2:3], off
